# same optimisations; the SWA relocation into phase 4 is now conditional on the 256-workgroup grid (other grid sizes keep the original phase-3 path)
# speedup vs baseline: 1.0005x; 1.0005x over previous
.LBB0_524:
	s_or_b64 exec, exec, s[10:11]
	s_cmpk_eq_i32 s33, 0x100
	s_cselect_b64 s[84:85], -1, 0
	s_cmpk_lg_i32 s33, 0x100
	v_lshlrev_b32_e32 v2, 4, v137
	s_cselect_b64 s[4:5], -1, 0
	v_and_b32_e32 v104, 15, v137
	v_and_b32_e32 v93, 0x70, v2
	v_lshrrev_b32_e32 v2, 4, v119
	v_writelane_b32 v255, s4, 7
	v_lshrrev_b32_e32 v105, 6, v137
	v_lshlrev_b32_e32 v99, 3, v2
	v_lshlrev_b32_e32 v106, 2, v2
	v_mul_u32_u24_e32 v2, 0x110, v104
	v_and_b32_e32 v3, 48, v119
	v_writelane_b32 v255, s5, 8
	s_movk_i32 s3, 0x200
	v_lshrrev_b32_e32 v94, 3, v137
	v_lshlrev_b32_e32 v71, 4, v105
	s_movk_i32 s4, 0x1ff
	v_add3_u32 v100, 0, v2, v3
	s_cmpk_lt_i32 s2, 0x200
	v_mov_b32_e32 v65, 0
	s_mov_b32 s89, 0
	v_lshl_add_u32 v91, v93, 1, 0
	v_mul_u32_u24_e32 v92, 0x110, v94
	v_add_u32_e32 v95, 64, v94
	v_cmp_lt_u32_e64 s[4:5], s4, v137
	v_cmp_gt_u32_e64 s[6:7], s3, v137
	v_or_b32_e32 v96, 0x80, v94
	v_lshl_add_u32 v90, v119, 1, 0
	v_or_b32_e32 v97, 64, v119
	v_or_b32_e32 v98, 0x80, v119
	v_lshrrev_b32_e32 v110, 7, v137
	v_or_b32_e32 v108, 32, v104
	v_add_u32_e32 v101, 0x2200, v100
	v_or_b32_e32 v109, 64, v104
	v_add_u32_e32 v102, 0x4400, v100
	v_or_b32_e32 v107, 0x60, v104
	v_add_u32_e32 v103, 0x6600, v100
	v_lshlrev_b32_e32 v60, 1, v71
	v_lshlrev_b32_e32 v62, 1, v93
	s_barrier
	v_readlane_b32 s3, v255, 41
	s_cmp_lg_u32 s3, 0
	s_cbranch_scc1 .Lswa_run
	s_cmpk_eq_i32 s33, 0x100
	s_cbranch_scc1 .LBB0_552
.Lswa_run:
	v_lshlrev_b32_e32 v3, 5, v105
	v_and_or_b32 v111, v3, 32, v104
	s_load_dwordx2 s[10:11], s[0:1], 0xd8
	s_load_dwordx2 s[12:13], s[0:1], 0x98
	v_or_b32_e32 v112, 16, v111
	v_sub_u32_e32 v3, v111, v106
	v_add_u32_e32 v113, 0x80, v3
	v_sub_u32_e32 v3, v112, v106
	v_or_b32_e32 v129, 0x80, v3
	v_mul_u32_u24_e32 v3, 0x190, v104
	v_lshlrev_b32_e32 v66, 1, v106
	v_add3_u32 v130, 0, v3, v66
	v_mul_u32_u24_e32 v3, 0x190, v108
	v_add3_u32 v131, 0, v3, v66
	v_mul_u32_u24_e32 v3, 0x190, v109
	s_waitcnt lgkmcnt(0)
	s_add_u32 s90, s10, 0xa5b8000
	v_add3_u32 v133, 0, v3, v66
	v_mul_u32_u24_e32 v3, 0x190, v107
	s_addc_u32 s91, s11, 0
	s_movk_i32 s3, 0xc0
	v_mul_u32_u24_e32 v2, 0x1900, v105
	v_add3_u32 v134, 0, v3, v66
	s_add_u32 s92, s10, 0x63b8000
	v_lshlrev_b32_e32 v64, 2, v93
	v_mbcnt_lo_u32_b32 v3, -1, 0
	v_cmp_gt_u32_e64 s[8:9], s3, v96
	v_or_b32_e32 v114, 2, v106
	v_or_b32_e32 v115, 3, v106
	v_or_b32_e32 v116, 32, v106
	v_or_b32_e32 v117, 33, v106
	v_or_b32_e32 v118, 34, v106
	v_or_b32_e32 v120, 35, v106
	v_or_b32_e32 v121, 64, v106
	v_or_b32_e32 v122, 0x41, v106
	v_or_b32_e32 v123, 0x42, v106
	v_or_b32_e32 v124, 0x43, v106
	v_or_b32_e32 v125, 0x60, v106
	v_or_b32_e32 v126, 0x61, v106
	v_or_b32_e32 v127, 0x62, v106
	v_or_b32_e32 v128, 0x63, v106
	v_add_u32_e32 v132, 0xcc00, v130
	s_addc_u32 s93, s11, 0
	v_lshl_add_u64 v[68:69], s[12:13], 0, v[64:65]
	s_add_i32 s3, s2, 0xffffff80
	s_lshl_b32 s87, s33, 6
	s_cmpk_eq_i32 s33, 0x100
	s_cselect_b32 s3, s3, s2
	s_cselect_b32 s87, 0x2000, s87
	s_lshl_b32 s3, s3, 6
	s_movk_i32 s86, 0x2c00
	s_mov_b64 s[94:95], 0x2a00
	s_movk_i32 s74, 0x2000
	s_mov_b64 s[96:97], 0x2800
	v_mov_b32_e32 v70, 0x358637bd
	s_mov_b32 s75, 0x800000
	v_mov_b64_e32 v[72:73], s[90:91]
	v_mov_b32_e32 v61, v65
	v_mov_b32_e32 v63, v65
	v_mbcnt_hi_u32_b32 v135, -1, v3
	v_add_u32_e32 v136, v90, v2
	v_mov_b32_e32 v138, 0x42800000
	v_not_b32_e32 v140, 63
	v_mov_b32_e32 v141, 0xff800000
	s_lshr_b32 s80, s3, 6
	s_branch .LBB0_527
.LBB0_526:
	s_or_b64 exec, exec, s[82:83]
	s_lshr_b32 s10, s87, 6
	s_add_i32 s80, s80, s10
	s_add_i32 s3, s3, s87
	s_cmpk_gt_i32 s80, 0x1ff
	s_cbranch_scc1 .LBB0_552

.LBB0_657:
	s_cmp_lt_i32 s78, 5
	s_cselect_b64 s[24:25], -1, 0
	s_and_b64 s[4:5], s[24:25], s[4:5]
	v_bfe_u32 v2, v0, 4, 2
	s_andn2_b64 vcc, exec, s[4:5]
	v_lshlrev_b32_e32 v254, 2, v2
	s_cbranch_vccnz .LBB0_814
	s_cmpk_lg_i32 s33, 0x100
	s_cbranch_scc1 .Lp4_after_swa
	s_cmpk_lt_u32 s2, 0x80
	s_cbranch_scc1 .Lp4_after_swa
	v_and_b32_e32 v137, 0x3ff, v0
	s_mov_b32 s3, 1
	v_and_b32_e32 v119, 63, v137
	v_writelane_b32 v255, s3, 41
	s_branch .LBB0_524
